# GEMM9 tile order: each XCD takes the 8-M-tile group that GEMM8 wrote last first (wgid ^= 64), so its A operand F is read while still cache resident
# baseline (speedup 1.0000x reference)
; #define PG8_BAR __builtin_amdgcn_s_barrier()
; template <int GI>
; __device__ __forceinline__ bool sched_next(unsigned char* ws, int i, int G, int c, GUnit& u) {
;     ...
;     const int L = i * G + c;
;     u.SA = 128 * d.ldc; u.SR = d.ldc; u.SB = 128; u.SX = 64; u.scale = d.scale;
;     if (d.kind == 0) {
;         constexpr int nwg = d.nM * d.nN;
;         if (L >= nwg) return false;
;         int wgid = L;
;         { constexpr int q = nwg / 8, r = nwg % 8; const int xcd = wgid % 8, off = wgid / 8; wgid = (xcd < r ? xcd * (q + 1) : r * (q + 1) + (xcd - r) * q) + off; }
;         constexpr int nig = 8 * d.nN; const int gid = wgid / nig, fm = gid * 8, gsz = (d.nM - fm) < 8 ? (d.nM - fm) : 8;
;         const int pm = fm + ((wgid % nig) % gsz), pn = (wgid % nig) / gsz;
;         u.A = (const char*)ws + d.A + (size_t)pm * d.a_tile;
;         u.B = (const char*)ws + d.B + (size_t)(pm >> 4) * d.b_batch + (size_t)pn * d.b_tile;
;         u.C = (char*)ws + d.C + (size_t)pm * d.c_rt + (size_t)pn * d.c_ct;
; template <int GI>
; __device__ __forceinline__ void gemm_phase(LAS unsigned char* lds, unsigned char* ws, int G, int cblk) {
;     ...
;     for (int i = 0; i < 2; ++i) { int R, C; stage_rc(tid * 16 + i * 8192, R, C); const int Rb = (R & ~31) + perm32(R & 31);
;         voffA[i] = (unsigned)(R * lda + C) * 2u; voffB[i] = (unsigned)(Rb * ldb + C) * 2u; }
;     const size_t kstep = (size_t)(BK * 2);
;     const size_t hstepA = (size_t)HALF * lda * 2, hstepB = (size_t)HALF * ldb * 2;
;     const unsigned ldsw = (unsigned)wid * 1024u;
;     const int aoff = lds_byte(wr * 64 + fr, fq * 8), boff = lds_byte(wc * 32 + fr, fq * 8);
;     ...
;     GUnit cur, nxt; int ui = 0;
;     if (!sched_next<GI>(ws, 0, G, cblk, cur)) return;
;     f32x4 acc[2][2][4][2];
; #pragma unroll
;     for (int a = 0; a < 2; ++a)
; #pragma unroll
;         for (int b = 0; b < 2; ++b)
; #pragma unroll
;             for (int m = 0; m < 4; ++m)
; #pragma unroll
;                 for (int n = 0; n < 2; ++n) acc[a][b][m][n] = (f32x4){0.f, 0.f, 0.f, 0.f};
;     bf16x8 At[4][2], B0[2][2], B1[2][2];
;     const char* cA = cur.A; const char* cB = cur.B;
;     PG8_STAGE(PG8_SB(0, 0), cB, voffB); PG8_STAGE(PG8_SB(0, 1), cB + hstepB, voffB); PG8_STAGE(PG8_SA(0, 0), cA, voffA); PG8_STAGE(PG8_SA(0, 1), cA + hstepA, voffA);
;     if (wr == 1) PG8_BAR;
.LBB0_884:
	v_ashrrev_i32_e32 v1, 31, v162
	v_lshrrev_b32_e32 v1, 26, v1
	v_add_u32_e32 v1, v162, v1
	v_ashrrev_i32_e32 v8, 6, v1
	v_bfe_i32 v1, v162, 27, 1
	v_lshlrev_b32_e32 v0, 4, v162
	v_lshrrev_b32_e32 v1, 22, v1
	v_add_u32_e32 v1, v0, v1
	v_and_b32_e32 v1, 0xfffffc00, v1
	v_sub_u32_e32 v1, v0, v1
	v_lshrrev_b32_e32 v2, 4, v1
	v_bitop3_b32 v1, v2, v1, 32 bitop3:0x6c
	v_ashrrev_i32_e32 v3, 31, v1
	v_lshrrev_b32_e32 v3, 26, v3
	v_lshlrev_b32_e32 v2, 3, v8
	v_add_u32_e32 v3, v1, v3
	v_and_b32_e32 v2, -16, v2
	v_ashrrev_i32_e32 v9, 6, v3
	v_and_b32_e32 v3, 0xc0, v3
	v_add_u32_e32 v2, v9, v2
	v_lshlrev_b32_e32 v4, 5, v8
	v_sub_u32_e32 v1, v1, v3
	v_mov_b32_e32 v3, 1
	v_and_b32_e32 v10, 32, v4
	v_ashrrev_i16_sdwa v1, v3, sext(v1) dst_sel:DWORD dst_unused:UNUSED_PAD src0_sel:DWORD src1_sel:BYTE_0
	v_lshlrev_b32_e32 v4, 1, v2
	v_lshrrev_b32_e32 v5, 2, v2
	v_and_b32_e32 v6, 3, v9
	s_mov_b32 s0, 0x7fffe0
	v_bfe_i32 v11, v1, 0, 16
	v_and_b32_e32 v4, 24, v4
	v_and_b32_e32 v5, 4, v5
	v_and_or_b32 v6, v2, s0, v6
	s_movk_i32 s6, 0x1600
	v_add_u32_e32 v1, v10, v11
	v_or3_b32 v4, v6, v5, v4
	v_mul_lo_u32 v2, v2, s6
	v_add_lshl_u32 v130, v1, v2, 1
	v_mul_u32_u24_e32 v2, 0x1600, v4
	v_add_u32_e32 v0, 0x2000, v0
	v_add_lshl_u32 v132, v2, v1, 1
	v_ashrrev_i32_e32 v1, 31, v0
	s_add_i32 s1, s1, s3
	s_xor_b32 s1, s1, 64
	v_lshrrev_b32_e32 v1, 22, v1
	s_ashr_i32 s3, s1, 31
	v_add_u32_e32 v1, v0, v1
	s_lshr_b32 s3, s3, 26
	v_ashrrev_i32_e32 v12, 10, v1
	s_add_i32 s3, s1, s3
	v_mul_i32_i24_e32 v1, 0x400, v12
	s_ashr_i32 s7, s3, 6
	s_and_b32 s3, s3, 0xffc0
	v_sub_u32_e32 v0, v0, v1
	s_sub_i32 s1, s1, s3
	v_lshrrev_b32_e32 v1, 4, v0
	s_bfe_i32 s3, s1, 0x80000
	v_bitop3_b32 v0, v1, v0, 32 bitop3:0x6c
	s_bfe_u32 s3, s3, 0x3000c
	v_ashrrev_i32_e32 v2, 31, v0
	s_add_i32 s3, s1, s3
	v_lshrrev_b32_e32 v2, 26, v2
	s_bfe_i32 s8, s3, 0x80000
	s_and_b32 s3, s3, 0xf8
	v_lshlrev_b32_e32 v1, 3, v12
	v_add_u32_e32 v2, v0, v2
	s_sub_i32 s1, s1, s3
	v_and_b32_e32 v1, -16, v1
	v_ashrrev_i32_e32 v13, 6, v2
	v_lshlrev_b32_e32 v4, 5, v12
	s_lshl_b32 s7, s7, 3
	s_sext_i32_i8 s1, s1
	s_ashr_i32 s15, s14, 6
	v_add_u32_e32 v1, v13, v1
	v_and_b32_e32 v14, 32, v4
	v_and_b32_e32 v4, 3, v13
	s_sext_i32_i16 s9, s8
	s_add_i32 s10, s7, s1
	v_and_or_b32 v4, v1, s0, v4
	s_ashr_i32 s18, s14, 8
	s_lshl_b32 s0, s15, 10
	s_lshr_b32 s8, s9, 3
	s_ashr_i32 s11, s10, 31
	s_mul_i32 s3, s10, 0x2c0000
	s_mul_hi_i32 s1, s10, 0x2c0000
	s_add_u32 s38, s35, s3
	s_addc_u32 s39, s46, s1
	s_add_u32 s1, s28, 0x6e00000
	v_and_b32_e32 v2, 0xc0, v2
	s_addc_u32 s3, s29, 0
	s_ashr_i32 s7, s9, 3
	v_sub_u32_e32 v0, v0, v2
	s_bfe_i64 s[12:13], s[8:9], 0x100000
	s_mul_hi_i32 s8, s7, 0x2c0000
	s_mul_i32 s7, s7, 0x2c0000
	v_ashrrev_i16_sdwa v0, v3, sext(v0) dst_sel:DWORD dst_unused:UNUSED_PAD src0_sel:DWORD src1_sel:BYTE_0
	v_lshlrev_b32_e32 v2, 1, v1
	v_lshrrev_b32_e32 v3, 2, v1
	s_add_u32 s40, s1, s7
	v_bfe_i32 v15, v0, 0, 16
	v_and_b32_e32 v2, 24, v2
	v_and_b32_e32 v3, 4, v3
	s_addc_u32 s41, s3, s8
	s_add_i32 s24, s0, 0
	v_add_u32_e32 v0, v14, v15
	v_or3_b32 v2, v4, v3, v2
	v_mul_lo_u32 v1, v1, s6
	s_add_i32 m0, s24, 0x10000
	v_add_lshl_u32 v134, v0, v1, 1
	v_mul_u32_u24_e32 v1, 0x1600, v2
	global_load_lds_dwordx4 v132, s[40:41]
	s_add_i32 m0, s24, 0x12000
	v_add_lshl_u32 v136, v1, v0, 1
	s_add_u32 s8, s40, 0x160000
	global_load_lds_dwordx4 v136, s[40:41]
	s_addc_u32 s9, s41, 0
	s_add_i32 m0, s24, 0x14000
	s_add_i32 s25, s24, 0x2000
	global_load_lds_dwordx4 v132, s[8:9]
	s_add_i32 m0, s24, 0x16000
	v_mov_b32_e32 v139, 0
	global_load_lds_dwordx4 v136, s[8:9]
	s_mov_b32 m0, s24
	s_add_u32 s8, s38, 0x160000
	global_load_lds_dwordx4 v130, s[38:39]
	s_mov_b32 m0, s25
	s_addc_u32 s9, s39, 0
	s_add_i32 s26, s24, 0x4000
	global_load_lds_dwordx4 v134, s[38:39]
	s_mov_b32 m0, s26
	s_add_i32 s27, s24, 0x6000
	global_load_lds_dwordx4 v130, s[8:9]
	s_mov_b32 m0, s27
	v_mov_b32_e32 v133, v139
	global_load_lds_dwordx4 v134, s[8:9]
	v_mov_b32_e32 v137, v139
	v_mov_b32_e32 v131, v139
	v_mov_b32_e32 v135, v139
	s_cmp_eq_u32 s18, 1
	s_mov_b32 s7, 0
	v_lshl_add_u64 v[6:7], s[40:41], 0, v[132:133]
	v_lshl_add_u64 v[2:3], s[40:41], 0, v[136:137]
	s_mov_b32 s19, 0x16000
	v_lshl_add_u64 v[0:1], s[38:39], 0, v[130:131]
	s_cselect_b64 s[8:9], -1, 0
	s_cmp_lg_u32 s18, 1
	v_lshl_add_u64 v[4:5], s[38:39], 0, v[134:135]
	s_cbranch_scc1 .LBB0_886
	s_barrier

; template <int GI>
; __device__ __forceinline__ bool sched_next(unsigned char* ws, int i, int G, int c, GUnit& u) {
;     ...
;         constexpr int nwg = d.nM * d.nN;
;         if (L >= nwg) return false;
;         int wgid = L;
;         { constexpr int q = nwg / 8, r = nwg % 8; const int xcd = wgid % 8, off = wgid / 8; wgid = (xcd < r ? xcd * (q + 1) : r * (q + 1) + (xcd - r) * q) + off; }
;         constexpr int nig = 8 * d.nN; const int gid = wgid / nig, fm = gid * 8, gsz = (d.nM - fm) < 8 ? (d.nM - fm) : 8;
;         const int pm = fm + ((wgid % nig) % gsz), pn = (wgid % nig) / gsz;
;         u.A = (const char*)ws + d.A + (size_t)pm * d.a_tile;
;         u.B = (const char*)ws + d.B + (size_t)(pm >> 4) * d.b_batch + (size_t)pn * d.b_tile;
;         u.C = (char*)ws + d.C + (size_t)pm * d.c_rt + (size_t)pn * d.c_ct;
.LBB0_894:
	s_ashr_i32 s15, s15, 3
	s_add_i32 s15, s23, s15
	s_xor_b32 s15, s15, 64
	s_ashr_i32 s20, s15, 31
	s_lshr_b32 s20, s20, 26
	s_add_i32 s20, s15, s20
	s_ashr_i32 s21, s20, 6
	s_and_b32 s20, s20, 0xffc0
	s_sub_i32 s15, s15, s20
	s_bfe_i32 s20, s15, 0x80000
	s_bfe_u32 s20, s20, 0x3000c
	s_add_i32 s20, s15, s20
	s_bfe_i32 s22, s20, 0x80000
	s_and_b32 s20, s20, 0xf8
	s_sub_i32 s15, s15, s20
	s_lshl_b32 s21, s21, 3
	s_sext_i32_i8 s15, s15
	s_sext_i32_i16 s23, s22
	s_add_i32 s36, s21, s15
	s_lshr_b32 s22, s23, 3
	s_ashr_i32 s37, s36, 31
	s_mul_i32 s20, s36, 0x2c0000
	s_mul_hi_i32 s15, s36, 0x2c0000
	s_add_u32 s20, s35, s20
	s_addc_u32 s21, s46, s15
	s_ashr_i32 s15, s23, 3
	s_bfe_i64 s[42:43], s[22:23], 0x100000
	s_mul_hi_i32 s23, s15, 0x2c0000
	s_mul_i32 s15, s15, 0x2c0000
	s_add_u32 s22, s1, s15
	s_addc_u32 s23, s3, s23
	s_lshl_b64 s[36:37], s[36:37], 20
	s_add_u32 s15, s33, s36
	s_addc_u32 s34, s47, s37
	s_lshl_b64 s[36:37], s[42:43], 9
	s_add_u32 s36, s15, s36
	s_addc_u32 s37, s34, s37
